# masked diagonal tile: removed six PV MFMAs whose probability operand is identically zero; shorter MFMA-to-VALU pad in the VALU half
# speedup vs baseline: 1.0071x; 1.0071x over previous
; #define LAS __attribute__((address_space(3)))
; __device__ __forceinline__ void attn_item(const Params& p, int l, LAS unsigned char* lds, int b, int h, int J) {
;     ...
; #pragma nounroll
;     for (int j = 0; j < blk_nt; ++j) {
;         LAS unsigned char* cur = lds + (j & 1) * ATT_BUF; LAS unsigned char* nxt = lds + ((j + 1) & 1) * ATT_BUF;
;         const bool more = (j + 1) < blk_nt;
;         if (more) { skn = *(const u32x4*)(gkn + (size_t)(j + 1) * 64 * 512); svt = *(const u32x4*)(gvt + (size_t)(j + 1) * 512 * 64); if (has_kr) skr = *(const u32x4*)(gkr + (size_t)(j + 1) * 64 * 256); }
;         if (j < my_nt) {
;             bf16x8 ka[2][6], va[2][4];
; #pragma unroll
;             for (int kb = 0; kb < 2; ++kb)
; #pragma unroll
;                 for (int s = 0; s < 6; ++s) ka[kb][s] = *(const LAS bf16x8*)(cur + rk + kb * 32 * KROW + 32 * s);
; #pragma unroll
;             for (int dvb = 0; dvb < 2; ++dvb)
; #pragma unroll
;                 for (int ks = 0; ks < 4; ++ks) va[dvb][ks] = *(const LAS bf16x8*)(cur + rv + dvb * 32 * VROW + 32 * ks);
;             __builtin_amdgcn_sched_barrier(0);
;             if (j < my_nt - 1) attn_step<false>(ka, va, qf, 64, lane, o0, o1, mrun, lsum); else attn_step<true>(ka, va, qf, 16, lane, o0, o1, mrun, lsum);
;         }
;         if (more) { *(LAS u32x4*)(nxt + wkn) = skn; *(LAS u32x4*)(nxt + wvt) = svt; if (has_kr) *(LAS u32x4*)(nxt + wkr) = skr; }
.Latt_head:
	s_add_i32 s12, s13, 1
	s_cmp_ge_i32 s13, s11
	s_cbranch_scc1 .Latt_skip_e
	s_bitcmp1_b32 s13, 0
	s_cselect_b32 s14, 0x5800, 0
	v_add3_u32 v0, s14, v233, v236
	s_cmp_eq_u32 s13, 0
	s_cbranch_scc1 .Latt_first
	v_mfma_f32_32x32x16_bf16 v[18:33], v[158:161], v[82:85], v[18:33]
	ds_read_b128 v[186:189], v0
	ds_read_b128 v[182:185], v0 offset:32
	v_mfma_f32_32x32x16_bf16 v[2:17], v[162:165], v[82:85], v[2:17]
	ds_read_b128 v[178:181], v0 offset:64
	ds_read_b128 v[174:177], v0 offset:96
	v_mfma_f32_32x32x16_bf16 v[18:33], v[150:153], v[86:89], v[18:33]
	ds_read_b128 v[170:173], v0 offset:128
	ds_read_b128 v[166:169], v0 offset:160
	v_mfma_f32_32x32x16_bf16 v[2:17], v[154:157], v[86:89], v[2:17]
	ds_read_b128 v[50:53], v0 offset:6656
	ds_read_b128 v[206:209], v0 offset:6688
	v_mfma_f32_32x32x16_bf16 v[18:33], v[146:149], v[90:93], v[18:33]
	ds_read_b128 v[202:205], v0 offset:6720
	ds_read_b128 v[198:201], v0 offset:6752
	v_mfma_f32_32x32x16_bf16 v[2:17], v[142:145], v[90:93], v[2:17]
	ds_read_b128 v[194:197], v0 offset:6784
	ds_read_b128 v[190:193], v0 offset:6816
	s_cmp_lt_i32 s12, s5
	s_cbranch_scc0 .Latt_noe_h1
	s_bitcmp1_b32 s12, 0
	s_cselect_b32 s15, 0x5800, 0
	v_add_u32_e32 v0, s15, v234
	s_waitcnt vmcnt(1)
	ds_write_b128 v0, v[98:101]
	v_add_u32_e32 v0, s15, v238
	s_waitcnt vmcnt(0)
	ds_write_b128 v0, v[102:105] offset:13312
	s_and_saveexec_b64 s[50:51], s[40:41]
	v_add_u32_e32 v0, s15, v239
	ds_write_b128 v0, v[106:109] offset:128
	s_or_b64 exec, exec, s[50:51]

; template <bool MASKED>
; __device__ __forceinline__ void attn_step(const bf16x8 (&ka)[2][6], const bf16x8 (&va)[2][4], const bf16x8 (&qf)[6], int nvalid, int lane, f32x16& o0, f32x16& o1, float& mrun, float& lsum) {
;     ...
;     float mx = fmaxf(fmaxf(s0[0], s0[1]), s0[2]);
; #pragma unroll
;     for (int i = 3; i < 15; i += 2) mx = fmaxf(fmaxf(mx, s0[i]), s0[i + 1]);
;     mx = fmaxf(mx, s0[15]);
; #pragma unroll
;     for (int i = 0; i < 16; i += 2) mx = fmaxf(fmaxf(mx, s1[i]), s1[i + 1]);
.Latt_nold_main:
	s_nop 6
	v_max3_f32 v0, v66, v67, v68
	v_max3_f32 v83, v69, v70, v71
	v_max3_f32 v84, v50, v51, v52
	v_max3_f32 v85, v53, v54, v55
	v_max3_f32 v0, v0, v72, v73
	v_max3_f32 v83, v83, v74, v75
	v_max3_f32 v84, v84, v56, v57
	v_max3_f32 v85, v85, v58, v59
	v_max3_f32 v0, v0, v76, v77
	v_max3_f32 v83, v83, v78, v79
	v_max3_f32 v84, v84, v60, v61
	v_max3_f32 v85, v85, v62, v63
	v_max3_f32 v0, v0, v80, v81
	v_max3_f32 v84, v84, v64, v65
	v_max3_f32 v0, v0, v83, v84
	v_max_f32_e32 v0, v0, v85
	v_cmp_gt_f32_e32 vcc, v0, v212
	s_cbranch_vccz .Latt_softmax
	ds_bpermute_b32 v82, v235, v0
	s_waitcnt lgkmcnt(0)
	v_max3_f32 v82, v0, v82, v213
	v_exp_f32_e64 v84, -v82
	v_add_f32_e32 v250, v250, v82
	v_mov_b32_e32 v212, 0x41000000
	v_mul_f32_e32 v249, v249, v84
	v_pk_mul_f32 v[32:33], v[32:33], v[84:85] op_sel_hi:[1,0]
	v_pk_mul_f32 v[30:31], v[30:31], v[84:85] op_sel_hi:[1,0]
	v_pk_mul_f32 v[28:29], v[28:29], v[84:85] op_sel_hi:[1,0]
	v_pk_mul_f32 v[26:27], v[26:27], v[84:85] op_sel_hi:[1,0]
	v_pk_mul_f32 v[24:25], v[24:25], v[84:85] op_sel_hi:[1,0]
	v_pk_mul_f32 v[22:23], v[22:23], v[84:85] op_sel_hi:[1,0]
	v_pk_mul_f32 v[20:21], v[20:21], v[84:85] op_sel_hi:[1,0]
	v_pk_mul_f32 v[18:19], v[18:19], v[84:85] op_sel_hi:[1,0]
	v_pk_mul_f32 v[16:17], v[16:17], v[84:85] op_sel_hi:[1,0]
	v_pk_mul_f32 v[14:15], v[14:15], v[84:85] op_sel_hi:[1,0]
	v_pk_mul_f32 v[12:13], v[12:13], v[84:85] op_sel_hi:[1,0]
	v_pk_mul_f32 v[10:11], v[10:11], v[84:85] op_sel_hi:[1,0]
	v_pk_mul_f32 v[8:9], v[8:9], v[84:85] op_sel_hi:[1,0]
	v_pk_mul_f32 v[6:7], v[6:7], v[84:85] op_sel_hi:[1,0]
	v_pk_mul_f32 v[4:5], v[4:5], v[84:85] op_sel_hi:[1,0]
	v_pk_mul_f32 v[2:3], v[2:3], v[84:85] op_sel_hi:[1,0]
	v_mov_b32_e32 v213, 0
	v_xor_b32_e32 v34, 0x80000000, v250
	v_sub_f32_e32 v66, v66, v82
	v_sub_f32_e32 v67, v67, v82
	v_sub_f32_e32 v68, v68, v82
	v_sub_f32_e32 v69, v69, v82
	v_sub_f32_e32 v70, v70, v82
	v_sub_f32_e32 v71, v71, v82
	v_sub_f32_e32 v72, v72, v82
	v_sub_f32_e32 v73, v73, v82
	v_sub_f32_e32 v74, v74, v82
	v_sub_f32_e32 v75, v75, v82
	v_sub_f32_e32 v76, v76, v82
	v_sub_f32_e32 v77, v77, v82
	v_sub_f32_e32 v78, v78, v82
	v_sub_f32_e32 v79, v79, v82
	v_sub_f32_e32 v80, v80, v82
	v_sub_f32_e32 v81, v81, v82
	v_sub_f32_e32 v50, v50, v82
	v_sub_f32_e32 v51, v51, v82
	v_sub_f32_e32 v52, v52, v82
	v_sub_f32_e32 v53, v53, v82
	v_sub_f32_e32 v54, v54, v82
	v_sub_f32_e32 v55, v55, v82
	v_sub_f32_e32 v56, v56, v82
	v_sub_f32_e32 v57, v57, v82
	v_sub_f32_e32 v58, v58, v82
	v_sub_f32_e32 v59, v59, v82
	v_sub_f32_e32 v60, v60, v82
	v_sub_f32_e32 v61, v61, v82
	v_sub_f32_e32 v62, v62, v82
	v_sub_f32_e32 v63, v63, v82
	v_sub_f32_e32 v64, v64, v82
	v_sub_f32_e32 v65, v65, v82
	v_mov_b32_e32 v35, v34
	v_mov_b32_e32 v36, v34
	v_mov_b32_e32 v37, v34
	v_mov_b32_e32 v38, v34
	v_mov_b32_e32 v39, v34
	v_mov_b32_e32 v40, v34
	v_mov_b32_e32 v41, v34
	v_mov_b32_e32 v42, v34
	v_mov_b32_e32 v43, v34
	v_mov_b32_e32 v44, v34
	v_mov_b32_e32 v45, v34
	v_mov_b32_e32 v46, v34
	v_mov_b32_e32 v47, v34
	v_mov_b32_e32 v48, v34
	v_mov_b32_e32 v49, v34

; __device__ __forceinline__ unsigned pk2(float a, float b) { f32x2 v = {a, b}; bf16x2_t r = __builtin_convertvector(v, bf16x2_t); return __builtin_bit_cast(unsigned, r); }
; template <bool MASKED>
; __device__ __forceinline__ void attn_step(const bf16x8 (&ka)[2][6], const bf16x8 (&va)[2][4], const bf16x8 (&qf)[6], int nvalid, int lane, f32x16& o0, f32x16& o1, float& mrun, float& lsum) {
;     ...
;     {
;         const f32x2 m2 = {mrun, mrun}; f32x2 acc2 = {0.f, 0.f};
; #pragma unroll
;         for (int i = 0; i < 16; i += 2) {
;             f32x2 a = (f32x2){s0[i], s0[i + 1]} - m2, c = (f32x2){s1[i], s1[i + 1]} - m2;
;             a.x = __builtin_amdgcn_exp2f(a.x); a.y = __builtin_amdgcn_exp2f(a.y); c.x = __builtin_amdgcn_exp2f(c.x); c.y = __builtin_amdgcn_exp2f(c.y);
;             acc2 = acc2 + a; acc2 = acc2 + c;
;             s0[i] = a.x; s0[i + 1] = a.y; s1[i] = c.x; s1[i + 1] = c.y;
;         }
;         lsum += acc2.x + acc2.y;
;     }
;     bf16x8 pf[4];
;     { u32x4 w;
;       w.x = pk2(s0[0], s0[1]); w.y = pk2(s0[2], s0[3]); w.z = pk2(s0[4], s0[5]); w.w = pk2(s0[6], s0[7]); pf[0] = __builtin_bit_cast(bf16x8, w);
;       w.x = pk2(s0[8], s0[9]); w.y = pk2(s0[10], s0[11]); w.z = pk2(s0[12], s0[13]); w.w = pk2(s0[14], s0[15]); pf[1] = __builtin_bit_cast(bf16x8, w);
;       w.x = pk2(s1[0], s1[1]); w.y = pk2(s1[2], s1[3]); w.z = pk2(s1[4], s1[5]); w.w = pk2(s1[6], s1[7]); pf[2] = __builtin_bit_cast(bf16x8, w);
;       w.x = pk2(s1[8], s1[9]); w.y = pk2(s1[10], s1[11]); w.z = pk2(s1[12], s1[13]); w.w = pk2(s1[14], s1[15]); pf[3] = __builtin_bit_cast(bf16x8, w); }
; #pragma unroll
;     for (int ks = 0; ks < 4; ++ks) { o0 = __builtin_amdgcn_mfma_f32_32x32x16_bf16(va[0][ks], pf[ks], o0, 0, 0, 0); o1 = __builtin_amdgcn_mfma_f32_32x32x16_bf16(va[1][ks], pf[ks], o1, 0, 0, 0); }
.LBB0_629:
	v_pk_add_f32 v[34:35], v[34:35], v[0:1] op_sel_hi:[1,0] neg_lo:[0,1] neg_hi:[0,1]
	v_mov_b32_e32 v213, v250
	v_exp_f32_e32 v42, v34
	v_exp_f32_e32 v43, v35
	v_pk_add_f32 v[34:35], v[36:37], v[0:1] op_sel_hi:[1,0] neg_lo:[0,1] neg_hi:[0,1]
	s_nop 0
	v_exp_f32_e32 v44, v34
	v_exp_f32_e32 v45, v35
	v_pk_add_f32 v[34:35], v[38:39], v[0:1] op_sel_hi:[1,0] neg_lo:[0,1] neg_hi:[0,1]
	s_nop 0
	v_exp_f32_e32 v38, v34
	v_exp_f32_e32 v39, v35
	v_pk_add_f32 v[34:35], v[40:41], v[0:1] op_sel_hi:[1,0] neg_lo:[0,1] neg_hi:[0,1]
	v_sub_f32_e32 v0, 0xff800000, v0
	v_exp_f32_e32 v40, v34
	v_exp_f32_e32 v41, v35
	v_cvt_pk_bf16_f32 v34, v42, v43
	v_cvt_pk_bf16_f32 v35, v44, v45
	v_cvt_pk_bf16_f32 v36, v38, v39
	v_cvt_pk_bf16_f32 v37, v40, v41
	v_exp_f32_e32 v0, v0
	s_waitcnt lgkmcnt(7)
	v_mfma_f32_32x32x16_bf16 v[18:33], v[158:161], v[34:37], v[18:33]
	v_cvt_pk_bf16_f32 v50, v0, v0
	v_mov_b32_e32 v51, v50
	v_mov_b32_e32 v52, v50
	v_mov_b32_e32 v53, v50
	s_waitcnt lgkmcnt(3)
	v_mfma_f32_32x32x16_bf16 v[2:17], v[162:165], v[34:37], v[2:17]
	v_add_f32_e64 v34, v42, 0
	v_add_f32_e64 v35, v43, 0
	v_add_f32_e64 v34, v0, v34
	v_add_f32_e64 v35, v0, v35
	v_add_f32_e64 v34, v44, v34
	v_add_f32_e64 v35, v45, v35
	v_pk_add_f32 v[34:35], v[0:1], v[34:35] op_sel_hi:[0,1]
	v_pk_add_f32 v[34:35], v[38:39], v[34:35]
	v_add_f32_e64 v34, v0, v34
	v_add_f32_e64 v35, v0, v35
	v_add_f32_e64 v34, v40, v34
	v_add_f32_e64 v35, v41, v35
	v_add_f32_e64 v34, v0, v34
	v_add_f32_e64 v35, v0, v35
	v_pk_add_f32 v[34:35], v[0:1], v[34:35] op_sel_hi:[0,1]
	v_pk_add_f32 v[34:35], v[0:1], v[34:35] op_sel_hi:[0,1]
	v_pk_add_f32 v[34:35], v[0:1], v[34:35] op_sel_hi:[0,1]
	s_waitcnt lgkmcnt(2)
	v_add_f32_e64 v34, v0, v34
	v_add_f32_e64 v35, v0, v35
	v_add_f32_e64 v34, v0, v34
	v_add_f32_e64 v35, v0, v35
	v_add_f32_e64 v34, v0, v34
	v_add_f32_e64 v35, v0, v35
	v_pk_add_f32 v[34:35], v[0:1], v[34:35] op_sel_hi:[0,1]
	v_pk_add_f32 v[34:35], v[0:1], v[34:35] op_sel_hi:[0,1]
	v_add_f32_e32 v0, v34, v35
	v_add_f32_e32 v249, v249, v0
	s_waitcnt lgkmcnt(1)
	s_waitcnt lgkmcnt(0)
	s_branch .Latt_end
